# v28 + merge-GEMM k-loops: segment-switch control block, parity move and next-tile read bases moved in front of the k-tile barrier
# speedup vs baseline: 1.0129x; 1.0017x over previous
; DI f32x4 mfma16(bf16x8 a, bf16x8 b, f32x4 c) { return __builtin_amdgcn_mfma_f32_16x16x32_bf16(a, b, c, 0, 0, 0); }
; DI void merge_tile(const Params& p, int layer, int tm, int tn, bf16_t* smem) {
;     ...
;   auto gload_next = [&]() {
;     const bf16_t* ab = la + (size_t)lkt * laks; const bf16_t* bb = lb + (size_t)lkt * 64;
; #pragma unroll
;     for (int i = 0; i < 4; ++i) ra[i] = *(const u32x4*)(ab + pa0 + (size_t)i * 64 * lald);
; #pragma unroll
;     for (int i = 0; i < 2; ++i) rb[i] = *(const u32x4*)(bb + pb0 + (size_t)i * 64 * lbld);
;     if (++lkt == lnk) {
;       if (ls + 1 < 6) { ++ls; lkt = 0; get_seg(ls); set_offsets(); } else lkt = lnk - 1;
;     }
;   };
;   auto sstore = [&](int buf) {
;     bf16_t* As = smem + buf * L::STAGE; bf16_t* Bs = As + L::A_ELEMS;
; #pragma unroll
;     for (int i = 0; i < 4; ++i) { const int c = tid + NTHR * i; *(u32x4*)(As + (c >> 3) * LDT + (c & 7) * 8) = ra[i]; }
; #pragma unroll
;     for (int i = 0; i < 2; ++i) { const int c = tid + NTHR * i; *(u32x4*)(Bs + (c >> 3) * LDT + (c & 7) * 8) = rb[i]; }
;   };
;   gload_next(); sstore(0); gload_next(); __syncthreads();
;   int buf = 0;
; #pragma unroll 1
;   for (int sg = 0; sg < 6; ++sg) {
;     const int nk = (sg & 1) ? 8 : 16;
; #pragma unroll 1
;     for (int kt = 0; kt < nk; ++kt) {
;       sstore(buf ^ 1);
;       gload_next();
;       __builtin_amdgcn_sched_barrier(0);
;       const bf16_t* As = smem + buf * L::STAGE + (wm * 128 + l15) * LDT + quad * 8;
;       const bf16_t* Bs = smem + buf * L::STAGE + L::A_ELEMS + (wn * 32 + l15) * LDT + quad * 8;
; #pragma unroll
;       for (int ks = 0; ks < 2; ++ks) {
;         if (ks == 1) asm volatile("" ::: "memory");
;         bf16x8 b[2];
; #pragma unroll
;         for (int j = 0; j < 2; ++j) b[j] = *(const bf16x8*)(Bs + j * 16 * LDT + ks * 32);
; #pragma unroll
;         for (int i = 0; i < 8; ++i) {
;           const bf16x8 a = *(const bf16x8*)(As + i * 16 * LDT + ks * 32);
; #pragma unroll
;           for (int j = 0; j < 2; ++j) acc[i][j] = mfma16(b[j], a, acc[i][j]);
;         }
;       }
;       __syncthreads();
.Lmg0_main:
	ds_read_b128 v[178:181], v165 offset:9216
	s_waitcnt lgkmcnt(2)
	v_mfma_f32_16x16x32_bf16 v[148:151], v[152:155], v[156:159], v[148:151]
	s_waitcnt lgkmcnt(1)
	v_mfma_f32_16x16x32_bf16 v[144:147], v[160:163], v[156:159], v[144:147]
	s_xor_b32 s44, s45, 1
	s_mul_i32 s15, s44, 0xd800
	v_add3_u32 v202, s15, v232, v229
	s_waitcnt vmcnt(5)
	ds_write_b128 v202, v[4:7]
	ds_read_b128 v[182:185], v165 offset:11520
	ds_read_b128 v[194:197], v164 offset:36928
	ds_read_b128 v[198:201], v164 offset:39232
	v_mfma_f32_16x16x32_bf16 v[140:143], v[152:155], v[166:169], v[140:143]
	v_mfma_f32_16x16x32_bf16 v[136:139], v[160:163], v[166:169], v[136:139]
	v_add3_u32 v4, s15, v233, v229
	s_waitcnt vmcnt(4)
	ds_write_b128 v4, v[0:3]
	ds_read_b128 v[186:189], v165 offset:13824
	v_mfma_f32_16x16x32_bf16 v[132:135], v[152:155], v[170:173], v[132:135]
	v_add3_u32 v0, s15, v234, v229
	s_ashr_i32 s21, s20, 31
	s_waitcnt vmcnt(3)
	ds_write_b128 v0, v[12:15]
	v_mfma_f32_16x16x32_bf16 v[128:131], v[160:163], v[170:173], v[128:131]
	ds_read_b128 v[190:193], v165 offset:16128
	v_mfma_f32_16x16x32_bf16 v[124:127], v[152:155], v[174:177], v[124:127]
	v_add3_u32 v0, s15, v235, v229
	s_mul_hi_u32 s15, s41, s20
	s_mul_i32 s46, s41, s21
	s_add_i32 s47, s15, s46
	s_mul_i32 s46, s41, s20
	s_lshl_b64 s[46:47], s[46:47], 1
	s_add_u32 s46, s18, s46
	s_addc_u32 s47, s19, s47
	s_waitcnt vmcnt(2)
	ds_write_b128 v0, v[8:11]
	v_mfma_f32_16x16x32_bf16 v[120:123], v[160:163], v[174:177], v[120:123]
	ds_read_b128 v[156:159], v165 offset:64
	s_waitcnt lgkmcnt(10)
	v_mfma_f32_16x16x32_bf16 v[116:119], v[152:155], v[178:181], v[116:119]
	s_waitcnt vmcnt(1)
	ds_write_b128 v202, v[16:19] offset:36864
	v_mfma_f32_16x16x32_bf16 v[112:115], v[160:163], v[178:181], v[112:115]
	ds_read_b128 v[166:169], v165 offset:2368
	s_waitcnt lgkmcnt(10)
	v_mfma_f32_16x16x32_bf16 v[108:111], v[152:155], v[182:185], v[108:111]
	s_waitcnt vmcnt(0)
	ds_write_b128 v4, v[20:23] offset:36864
	v_mfma_f32_16x16x32_bf16 v[104:107], v[160:163], v[182:185], v[104:107]
	v_lshl_add_u64 v[0:1], v[216:217], 1, s[46:47]
	s_lshl_b64 s[46:47], s[2:3], 7
	v_lshl_add_u64 v[8:9], v[0:1], 0, s[46:47]
	s_lshl_b64 s[48:49], s[20:21], 7
	global_load_dwordx4 v[4:7], v[0:1], off
	ds_read_b128 v[170:173], v165 offset:4672
	s_waitcnt lgkmcnt(8)
	v_mfma_f32_16x16x32_bf16 v[100:103], v[152:155], v[186:189], v[100:103]
	v_mfma_f32_16x16x32_bf16 v[96:99], v[160:163], v[186:189], v[96:99]
	s_nop 0
	global_load_dwordx4 v[0:3], v[8:9], off
	ds_read_b128 v[174:177], v165 offset:6976
	s_waitcnt lgkmcnt(7)
	v_mfma_f32_16x16x32_bf16 v[92:95], v[152:155], v[190:193], v[92:95]
	v_mfma_f32_16x16x32_bf16 v[88:91], v[160:163], v[190:193], v[88:91]
	v_lshl_add_u64 v[8:9], v[8:9], 0, s[46:47]
	v_lshl_add_u64 v[10:11], v[8:9], 0, s[46:47]
	s_add_u32 s46, s16, s48
	s_addc_u32 s47, s17, s49
	v_mov_b32_e32 v219, v217
	s_mov_b32 s15, s3
	v_lshl_add_u64 v[16:17], v[218:219], 1, s[46:47]
	s_lshl_b64 s[46:47], s[14:15], 7
	v_lshl_add_u64 v[20:21], v[16:17], 0, s[46:47]
	global_load_dwordx4 v[12:15], v[8:9], off
	ds_read_b128 v[178:181], v165 offset:9280
	s_waitcnt lgkmcnt(6)
	v_mfma_f32_16x16x32_bf16 v[148:151], v[194:197], v[156:159], v[148:151]
	s_nop 0
	global_load_dwordx4 v[8:11], v[10:11], off
	v_mfma_f32_16x16x32_bf16 v[144:147], v[198:201], v[156:159], v[144:147]
	ds_read_b128 v[182:185], v165 offset:11584
	s_waitcnt lgkmcnt(5)
	v_mfma_f32_16x16x32_bf16 v[140:143], v[194:197], v[166:169], v[140:143]
	s_nop 0
	global_load_dwordx4 v[16:19], v[16:17], off
	v_mfma_f32_16x16x32_bf16 v[136:139], v[198:201], v[166:169], v[136:139]
	s_nop 0
	global_load_dwordx4 v[20:23], v[20:21], off
	ds_read_b128 v[186:189], v165 offset:13888
	s_waitcnt lgkmcnt(4)
	v_mfma_f32_16x16x32_bf16 v[132:135], v[194:197], v[170:173], v[132:135]
	v_mfma_f32_16x16x32_bf16 v[128:131], v[198:201], v[170:173], v[128:131]
	ds_read_b128 v[190:193], v165 offset:16192
	s_waitcnt lgkmcnt(4)
	v_mfma_f32_16x16x32_bf16 v[124:127], v[194:197], v[174:177], v[124:127]
	v_mfma_f32_16x16x32_bf16 v[120:123], v[198:201], v[174:177], v[120:123]
	s_add_i32 s15, s20, 1
	s_cmp_lg_u32 s15, s42
	s_cbranch_scc1 .LBB0_842
	s_cmp_gt_i32 s43, 4
	s_cbranch_scc1 .LBB0_845
	s_add_i32 s21, s43, 1
	s_ashr_i32 s18, s21, 1
	s_bitcmp0_b32 s43, 0
	s_mov_b64 s[14:15], -1
	s_cbranch_scc1 .LBB0_840
	s_ashr_i32 s19, s18, 31
	s_lshl_b64 s[14:15], s[18:19], 21
	s_add_u32 s16, s10, s14
	s_addc_u32 s17, s11, s15
	s_mov_b64 s[14:15], 0

; DI f32x4 mfma16(bf16x8 a, bf16x8 b, f32x4 c) { return __builtin_amdgcn_mfma_f32_16x16x32_bf16(a, b, c, 0, 0, 0); }
; DI void merge_tile(const Params& p, int layer, int tm, int tn, bf16_t* smem) {
;     ...
;     if (++lkt == lnk) {
;       if (ls + 1 < 6) { ++ls; lkt = 0; get_seg(ls); set_offsets(); } else lkt = lnk - 1;
;     }
;   };
;   auto sstore = [&](int buf) {
;     bf16_t* As = smem + buf * L::STAGE; bf16_t* Bs = As + L::A_ELEMS;
; #pragma unroll
;     for (int i = 0; i < 4; ++i) { const int c = tid + NTHR * i; *(u32x4*)(As + (c >> 3) * LDT + (c & 7) * 8) = ra[i]; }
; #pragma unroll
;     for (int i = 0; i < 2; ++i) { const int c = tid + NTHR * i; *(u32x4*)(Bs + (c >> 3) * LDT + (c & 7) * 8) = rb[i]; }
;   };
;   gload_next(); sstore(0); gload_next(); __syncthreads();
;   int buf = 0;
; #pragma unroll 1
;   for (int sg = 0; sg < 6; ++sg) {
;     const int nk = (sg & 1) ? 8 : 16;
; #pragma unroll 1
;     for (int kt = 0; kt < nk; ++kt) {
;       sstore(buf ^ 1);
;       gload_next();
;       __builtin_amdgcn_sched_barrier(0);
;       const bf16_t* As = smem + buf * L::STAGE + (wm * 128 + l15) * LDT + quad * 8;
;       const bf16_t* Bs = smem + buf * L::STAGE + L::A_ELEMS + (wn * 32 + l15) * LDT + quad * 8;
; #pragma unroll
;       for (int ks = 0; ks < 2; ++ks) {
;         if (ks == 1) asm volatile("" ::: "memory");
;         bf16x8 b[2];
; #pragma unroll
;         for (int j = 0; j < 2; ++j) b[j] = *(const bf16x8*)(Bs + j * 16 * LDT + ks * 32);
; #pragma unroll
;         for (int i = 0; i < 8; ++i) {
;           const bf16x8 a = *(const bf16x8*)(As + i * 16 * LDT + ks * 32);
; #pragma unroll
;           for (int j = 0; j < 2; ++j) acc[i][j] = mfma16(b[j], a, acc[i][j]);
;         }
;       }
;       __syncthreads();
;       buf ^= 1;
.LBB0_845:
	s_add_i32 s33, s33, -1
	s_mov_b32 s45, s44
	s_mul_i32 s98, s45, 0xd800
	v_add3_u32 v164, s98, v231, v236
	v_add3_u32 v165, s98, v230, v236
	s_cmp_eq_u32 s33, 0
	s_waitcnt lgkmcnt(0)
	s_barrier
	s_cbranch_scc1 .Lmg0_exit
	ds_read_b128 v[156:159], v165
	ds_read_b128 v[166:169], v165 offset:2304
	ds_read_b128 v[170:173], v165 offset:4608
	ds_read_b128 v[174:177], v165 offset:6912
	ds_read_b128 v[152:155], v164 offset:36864
	ds_read_b128 v[160:163], v164 offset:39168
	v_mfma_f32_16x16x32_bf16 v[116:119], v[194:197], v[178:181], v[116:119]
	v_mfma_f32_16x16x32_bf16 v[108:111], v[194:197], v[182:185], v[108:111]
	v_mfma_f32_16x16x32_bf16 v[100:103], v[194:197], v[186:189], v[100:103]
	v_mfma_f32_16x16x32_bf16 v[92:95], v[194:197], v[190:193], v[92:95]
	v_mfma_f32_16x16x32_bf16 v[112:115], v[198:201], v[178:181], v[112:115]
	v_mfma_f32_16x16x32_bf16 v[104:107], v[198:201], v[182:185], v[104:107]
	v_mfma_f32_16x16x32_bf16 v[96:99], v[198:201], v[186:189], v[96:99]
	v_mfma_f32_16x16x32_bf16 v[88:91], v[198:201], v[190:193], v[88:91]
	s_branch .Lmg0_main

; DI f32x4 mfma16(bf16x8 a, bf16x8 b, f32x4 c) { return __builtin_amdgcn_mfma_f32_16x16x32_bf16(a, b, c, 0, 0, 0); }
; DI void merge_tile(const Params& p, int layer, int tm, int tn, bf16_t* smem) {
;     ...
;   auto gload_next = [&]() {
;     const bf16_t* ab = la + (size_t)lkt * laks; const bf16_t* bb = lb + (size_t)lkt * 64;
; #pragma unroll
;     for (int i = 0; i < 4; ++i) ra[i] = *(const u32x4*)(ab + pa0 + (size_t)i * 64 * lald);
; #pragma unroll
;     for (int i = 0; i < 2; ++i) rb[i] = *(const u32x4*)(bb + pb0 + (size_t)i * 64 * lbld);
;     if (++lkt == lnk) {
;       if (ls + 1 < 6) { ++ls; lkt = 0; get_seg(ls); set_offsets(); } else lkt = lnk - 1;
;     }
;   };
;   auto sstore = [&](int buf) {
;     bf16_t* As = smem + buf * L::STAGE; bf16_t* Bs = As + L::A_ELEMS;
; #pragma unroll
;     for (int i = 0; i < 4; ++i) { const int c = tid + NTHR * i; *(u32x4*)(As + (c >> 3) * LDT + (c & 7) * 8) = ra[i]; }
; #pragma unroll
;     for (int i = 0; i < 2; ++i) { const int c = tid + NTHR * i; *(u32x4*)(Bs + (c >> 3) * LDT + (c & 7) * 8) = rb[i]; }
;   };
;   gload_next(); sstore(0); gload_next(); __syncthreads();
;   int buf = 0;
; #pragma unroll 1
;   for (int sg = 0; sg < 6; ++sg) {
;     const int nk = (sg & 1) ? 8 : 16;
; #pragma unroll 1
;     for (int kt = 0; kt < nk; ++kt) {
;       sstore(buf ^ 1);
;       gload_next();
;       __builtin_amdgcn_sched_barrier(0);
;       const bf16_t* As = smem + buf * L::STAGE + (wm * 128 + l15) * LDT + quad * 8;
;       const bf16_t* Bs = smem + buf * L::STAGE + L::A_ELEMS + (wn * 32 + l15) * LDT + quad * 8;
; #pragma unroll
;       for (int ks = 0; ks < 2; ++ks) {
;         if (ks == 1) asm volatile("" ::: "memory");
;         bf16x8 b[2];
; #pragma unroll
;         for (int j = 0; j < 2; ++j) b[j] = *(const bf16x8*)(Bs + j * 16 * LDT + ks * 32);
; #pragma unroll
;         for (int i = 0; i < 8; ++i) {
;           const bf16x8 a = *(const bf16x8*)(As + i * 16 * LDT + ks * 32);
; #pragma unroll
;           for (int j = 0; j < 2; ++j) acc[i][j] = mfma16(b[j], a, acc[i][j]);
;         }
;       }
;       __syncthreads();
.Lmg1_main:
	ds_read_b128 v[182:185], v168 offset:9216
	s_waitcnt lgkmcnt(2)
	v_mfma_f32_16x16x32_bf16 v[148:151], v[152:155], v[156:159], v[148:151]
	s_waitcnt lgkmcnt(1)
	v_mfma_f32_16x16x32_bf16 v[144:147], v[160:163], v[156:159], v[144:147]
	s_xor_b32 s55, s57, 1
	s_mul_i32 s2, s55, 0xd800
	v_add3_u32 v169, s2, v232, v229
	s_waitcnt vmcnt(5)
	ds_write_b128 v169, v[4:7]
	ds_read_b128 v[186:189], v168 offset:11520
	ds_read_b128 v[198:201], v164 offset:36928
	ds_read_b128 v[202:205], v164 offset:39232
	v_mfma_f32_16x16x32_bf16 v[140:143], v[152:155], v[170:173], v[140:143]
	v_mfma_f32_16x16x32_bf16 v[136:139], v[160:163], v[170:173], v[136:139]
	v_add3_u32 v4, s2, v233, v229
	s_waitcnt vmcnt(4)
	ds_write_b128 v4, v[0:3]
	ds_read_b128 v[190:193], v168 offset:13824
	v_mfma_f32_16x16x32_bf16 v[132:135], v[152:155], v[174:177], v[132:135]
	v_add3_u32 v0, s2, v234, v229
	s_ashr_i32 s27, s26, 31
	s_waitcnt vmcnt(3)
	ds_write_b128 v0, v[12:15]
	v_mfma_f32_16x16x32_bf16 v[128:131], v[160:163], v[174:177], v[128:131]
	ds_read_b128 v[194:197], v168 offset:16128
	v_mfma_f32_16x16x32_bf16 v[124:127], v[152:155], v[178:181], v[124:127]
	v_add3_u32 v0, s2, v235, v229
	s_mul_hi_u32 s2, s52, s26
	s_mul_i32 s3, s52, s27
	s_add_i32 s3, s2, s3
	s_mul_i32 s2, s52, s26
	s_lshl_b64 s[2:3], s[2:3], 1
	s_add_u32 s2, s24, s2
	s_addc_u32 s3, s25, s3
	s_waitcnt vmcnt(2)
	ds_write_b128 v0, v[8:11]
	v_mfma_f32_16x16x32_bf16 v[120:123], v[160:163], v[178:181], v[120:123]
	ds_read_b128 v[156:159], v168 offset:64
	s_waitcnt lgkmcnt(10)
	v_mfma_f32_16x16x32_bf16 v[116:119], v[152:155], v[182:185], v[116:119]
	s_waitcnt vmcnt(1)
	ds_write_b128 v169, v[16:19] offset:36864
	v_mfma_f32_16x16x32_bf16 v[112:115], v[160:163], v[182:185], v[112:115]
	ds_read_b128 v[170:173], v168 offset:2368
	s_waitcnt lgkmcnt(10)
	v_mfma_f32_16x16x32_bf16 v[108:111], v[152:155], v[186:189], v[108:111]
	s_waitcnt vmcnt(0)
	ds_write_b128 v4, v[20:23] offset:36864
	v_mfma_f32_16x16x32_bf16 v[104:107], v[160:163], v[186:189], v[104:107]
	v_lshl_add_u64 v[0:1], v[216:217], 1, s[2:3]
	s_lshl_b64 s[2:3], s[8:9], 7
	v_lshl_add_u64 v[8:9], v[0:1], 0, s[2:3]
	s_lshl_b64 s[4:5], s[26:27], 7
	global_load_dwordx4 v[4:7], v[0:1], off
	ds_read_b128 v[174:177], v168 offset:4672
	s_waitcnt lgkmcnt(8)
	v_mfma_f32_16x16x32_bf16 v[100:103], v[152:155], v[190:193], v[100:103]
	v_mfma_f32_16x16x32_bf16 v[96:99], v[160:163], v[190:193], v[96:99]
	s_nop 0
	global_load_dwordx4 v[0:3], v[8:9], off
	ds_read_b128 v[178:181], v168 offset:6976
	s_waitcnt lgkmcnt(7)
	v_mfma_f32_16x16x32_bf16 v[92:95], v[152:155], v[194:197], v[92:95]
	v_mfma_f32_16x16x32_bf16 v[88:91], v[160:163], v[194:197], v[88:91]
	v_lshl_add_u64 v[8:9], v[8:9], 0, s[2:3]
	v_lshl_add_u64 v[10:11], v[8:9], 0, s[2:3]
	s_add_u32 s2, s22, s4
	s_addc_u32 s3, s23, s5
	v_mov_b32_e32 v219, v217
	s_mov_b32 s21, s9
	v_lshl_add_u64 v[16:17], v[218:219], 1, s[2:3]
	s_lshl_b64 s[2:3], s[20:21], 7
	v_lshl_add_u64 v[20:21], v[16:17], 0, s[2:3]
	global_load_dwordx4 v[12:15], v[8:9], off
	ds_read_b128 v[182:185], v168 offset:9280
	s_waitcnt lgkmcnt(6)
	v_mfma_f32_16x16x32_bf16 v[148:151], v[198:201], v[156:159], v[148:151]
	s_nop 0
	global_load_dwordx4 v[8:11], v[10:11], off
	v_mfma_f32_16x16x32_bf16 v[144:147], v[202:205], v[156:159], v[144:147]
	ds_read_b128 v[186:189], v168 offset:11584
	s_waitcnt lgkmcnt(5)
	v_mfma_f32_16x16x32_bf16 v[140:143], v[198:201], v[170:173], v[140:143]
	s_nop 0
	global_load_dwordx4 v[16:19], v[16:17], off
	v_mfma_f32_16x16x32_bf16 v[136:139], v[202:205], v[170:173], v[136:139]
	s_nop 0
	global_load_dwordx4 v[20:23], v[20:21], off
	ds_read_b128 v[190:193], v168 offset:13888
	s_waitcnt lgkmcnt(4)
	v_mfma_f32_16x16x32_bf16 v[132:135], v[198:201], v[174:177], v[132:135]
	v_mfma_f32_16x16x32_bf16 v[128:131], v[202:205], v[174:177], v[128:131]
	ds_read_b128 v[194:197], v168 offset:16192
	s_waitcnt lgkmcnt(4)
	v_mfma_f32_16x16x32_bf16 v[124:127], v[198:201], v[178:181], v[124:127]
	v_mfma_f32_16x16x32_bf16 v[120:123], v[202:205], v[178:181], v[120:123]
	s_add_i32 s2, s26, 1
	s_cmp_lg_u32 s2, s53
	s_cbranch_scc1 .LBB0_1876
	s_cmp_gt_i32 s54, 4
	s_cbranch_scc1 .LBB0_1879
	s_add_i32 s21, s54, 1
	s_ashr_i32 s2, s21, 1
	s_bitcmp0_b32 s54, 0
	s_mov_b64 s[4:5], -1
	s_cbranch_scc1 .LBB0_1874
	s_ashr_i32 s3, s2, 31
	s_lshl_b64 s[4:5], s[2:3], 21
	s_add_u32 s22, s16, s4
	s_addc_u32 s23, s17, s5
	s_mov_b64 s[4:5], 0

; DI f32x4 mfma16(bf16x8 a, bf16x8 b, f32x4 c) { return __builtin_amdgcn_mfma_f32_16x16x32_bf16(a, b, c, 0, 0, 0); }
; DI void merge_tile(const Params& p, int layer, int tm, int tn, bf16_t* smem) {
;     ...
;     if (++lkt == lnk) {
;       if (ls + 1 < 6) { ++ls; lkt = 0; get_seg(ls); set_offsets(); } else lkt = lnk - 1;
;     }
;   };
;   auto sstore = [&](int buf) {
;     bf16_t* As = smem + buf * L::STAGE; bf16_t* Bs = As + L::A_ELEMS;
; #pragma unroll
;     for (int i = 0; i < 4; ++i) { const int c = tid + NTHR * i; *(u32x4*)(As + (c >> 3) * LDT + (c & 7) * 8) = ra[i]; }
; #pragma unroll
;     for (int i = 0; i < 2; ++i) { const int c = tid + NTHR * i; *(u32x4*)(Bs + (c >> 3) * LDT + (c & 7) * 8) = rb[i]; }
;   };
;   gload_next(); sstore(0); gload_next(); __syncthreads();
;   int buf = 0;
; #pragma unroll 1
;   for (int sg = 0; sg < 6; ++sg) {
;     const int nk = (sg & 1) ? 8 : 16;
; #pragma unroll 1
;     for (int kt = 0; kt < nk; ++kt) {
;       sstore(buf ^ 1);
;       gload_next();
;       __builtin_amdgcn_sched_barrier(0);
;       const bf16_t* As = smem + buf * L::STAGE + (wm * 128 + l15) * LDT + quad * 8;
;       const bf16_t* Bs = smem + buf * L::STAGE + L::A_ELEMS + (wn * 32 + l15) * LDT + quad * 8;
; #pragma unroll
;       for (int ks = 0; ks < 2; ++ks) {
;         if (ks == 1) asm volatile("" ::: "memory");
;         bf16x8 b[2];
; #pragma unroll
;         for (int j = 0; j < 2; ++j) b[j] = *(const bf16x8*)(Bs + j * 16 * LDT + ks * 32);
; #pragma unroll
;         for (int i = 0; i < 8; ++i) {
;           const bf16x8 a = *(const bf16x8*)(As + i * 16 * LDT + ks * 32);
; #pragma unroll
;           for (int j = 0; j < 2; ++j) acc[i][j] = mfma16(b[j], a, acc[i][j]);
;         }
;       }
;       __syncthreads();
;       buf ^= 1;
.LBB0_1879:
	s_add_i32 s56, s56, -1
	s_mov_b32 s57, s55
	s_mul_i32 s98, s57, 0xd800
	v_add3_u32 v164, s98, v231, v236
	v_add3_u32 v168, s98, v230, v236
	s_cmp_eq_u32 s56, 0
	s_waitcnt lgkmcnt(0)
	s_barrier
	s_cbranch_scc1 .Lmg1_exit
	ds_read_b128 v[156:159], v168
	ds_read_b128 v[170:173], v168 offset:2304
	ds_read_b128 v[174:177], v168 offset:4608
	ds_read_b128 v[178:181], v168 offset:6912
	ds_read_b128 v[152:155], v164 offset:36864
	ds_read_b128 v[160:163], v164 offset:39168
	v_mfma_f32_16x16x32_bf16 v[116:119], v[198:201], v[182:185], v[116:119]
	v_mfma_f32_16x16x32_bf16 v[108:111], v[198:201], v[186:189], v[108:111]
	v_mfma_f32_16x16x32_bf16 v[100:103], v[198:201], v[190:193], v[100:103]
	v_mfma_f32_16x16x32_bf16 v[92:95], v[198:201], v[194:197], v[92:95]
	v_mfma_f32_16x16x32_bf16 v[112:115], v[202:205], v[182:185], v[112:115]
	v_mfma_f32_16x16x32_bf16 v[104:107], v[202:205], v[186:189], v[104:107]
	v_mfma_f32_16x16x32_bf16 v[96:99], v[202:205], v[190:193], v[96:99]
	v_mfma_f32_16x16x32_bf16 v[88:91], v[202:205], v[194:197], v[88:91]
	s_branch .Lmg1_main
